# dense64 attention loop: next tile's global K/V loads issued before the closing barrier instead of after it (pointer re-base moved with them)
# speedup vs baseline: 1.0041x; 1.0041x over previous
.Lad64_noprio:
	v_add_u32_e32 v134, s3, v118
	v_mad_i64_i32 v[246:247], s[26:27], v134, s82, 0
	v_mov_b32_e32 v208, s86
	v_mov_b32_e32 v209, s87
	v_lshl_add_u64 v[208:209], v[246:247], 1, v[208:209]
	v_lshl_add_u64 v[208:209], v[208:209], 0, s[0:1]
	v_lshl_add_u64 v[240:241], v[92:93], 1, v[208:209]
	v_add_u32_e32 v134, s3, v117
	v_mad_i64_i32 v[246:247], s[26:27], v134, s82, 0
	v_mov_b32_e32 v208, s90
	v_mov_b32_e32 v209, s91
	v_lshl_add_u64 v[208:209], v[246:247], 1, v[208:209]
	v_lshl_add_u64 v[208:209], v[208:209], 0, s[0:1]
	v_lshl_add_u64 v[242:243], v[208:209], 0, v[0:1]
	s_lshl_b32 s26, s82, 7
	v_mov_b32_e32 v244, s26
	v_mov_b32_e32 v245, 0
	v_mov_b32_e32 v239, v118
	s_mov_b32 s2, 0x41000000
	v_sub_f32_e32 v118, 0, v112
	v_sub_f32_e32 v119, 0, v112
	v_sub_f32_e32 v120, 0, v112
	v_sub_f32_e32 v121, 0, v112
	v_sub_f32_e32 v122, 0, v112
	v_sub_f32_e32 v123, 0, v112
	v_sub_f32_e32 v124, 0, v112
	v_sub_f32_e32 v125, 0, v112
	v_sub_f32_e32 v126, 0, v112
	v_sub_f32_e32 v127, 0, v112
	v_sub_f32_e32 v128, 0, v112
	v_sub_f32_e32 v129, 0, v112
	v_sub_f32_e32 v130, 0, v112
	v_sub_f32_e32 v131, 0, v112
	v_sub_f32_e32 v132, 0, v112
	v_sub_f32_e32 v133, 0, v112
	s_add_i32 s25, s24, 0xffffc000
	s_and_b32 s25, s25, 0x4000
	v_add_u32_e32 v134, s25, v98
	v_add_u32_e32 v117, s25, v109
	v_add_u32_e32 v208, s25, v111
	v_add_u32_e32 v209, s25, v114
	global_load_dwordx4 v[82:85], v[240:241], off
	global_load_dwordx4 v[86:89], v[242:243], off
	v_lshl_add_u64 v[240:241], v[240:241], 0, v[244:245]
	v_lshl_add_u64 v[242:243], v[242:243], 0, v[244:245]
.Lad64_top:
	ds_read_b128 v[148:151], v134
	ds_read_b128 v[152:155], v117
	ds_read_b128 v[156:159], v208
	ds_read_b128 v[160:163], v209
	ds_read_b128 v[164:167], v134 offset:4096
	ds_read_b128 v[168:171], v117 offset:4096
	ds_read_b128 v[172:175], v208 offset:4096
	ds_read_b128 v[176:179], v209 offset:4096
	s_waitcnt lgkmcnt(7)
	v_mfma_f32_32x32x16_bf16 v[34:49], v[148:151], v[78:81], v[118:133]
	s_waitcnt lgkmcnt(6)
	v_mfma_f32_32x32x16_bf16 v[34:49], v[152:155], v[74:77], v[34:49]
	s_waitcnt lgkmcnt(5)
	v_mfma_f32_32x32x16_bf16 v[34:49], v[156:159], v[70:73], v[34:49]
	s_waitcnt lgkmcnt(4)
	v_mfma_f32_32x32x16_bf16 v[34:49], v[160:163], v[66:69], v[34:49]
	s_waitcnt lgkmcnt(3)
	v_mfma_f32_32x32x16_bf16 v[50:65], v[164:167], v[78:81], v[118:133]
	s_waitcnt lgkmcnt(2)
	v_mfma_f32_32x32x16_bf16 v[50:65], v[168:171], v[74:77], v[50:65]
	s_waitcnt lgkmcnt(1)
	v_mfma_f32_32x32x16_bf16 v[50:65], v[172:175], v[70:73], v[50:65]
	s_waitcnt lgkmcnt(0)
	v_mfma_f32_32x32x16_bf16 v[50:65], v[176:179], v[66:69], v[50:65]
	v_add3_u32 v134, s25, v115, v113
	v_add_u32_e32 v117, s25, v116
	ds_read_b64_tr_b16 v[180:181], v134 offset:8192
	ds_read_b64_tr_b16 v[182:183], v134 offset:9216
	ds_read_b64_tr_b16 v[184:185], v117 offset:8192
	ds_read_b64_tr_b16 v[186:187], v117 offset:9216
	ds_read_b64_tr_b16 v[188:189], v134 offset:10240
	ds_read_b64_tr_b16 v[190:191], v134 offset:11264
	ds_read_b64_tr_b16 v[192:193], v117 offset:10240
	ds_read_b64_tr_b16 v[194:195], v117 offset:11264
	ds_read_b64_tr_b16 v[196:197], v134 offset:12288
	ds_read_b64_tr_b16 v[198:199], v134 offset:13312
	ds_read_b64_tr_b16 v[200:201], v117 offset:12288
	ds_read_b64_tr_b16 v[202:203], v117 offset:13312
	v_max3_f32 v208, v34, v35, v36
	v_max3_f32 v208, v208, v37, v38
	v_max3_f32 v208, v208, v39, v40
	v_max3_f32 v208, v208, v41, v42
	v_max3_f32 v208, v208, v43, v44
	v_max3_f32 v208, v208, v45, v46
	v_max3_f32 v208, v208, v47, v48
	v_max3_f32 v209, v50, v51, v52
	v_max3_f32 v209, v209, v53, v54
	v_max3_f32 v209, v209, v55, v56
	v_max3_f32 v209, v209, v57, v58
	v_max3_f32 v209, v209, v59, v60
	v_max3_f32 v209, v209, v61, v62
	v_max3_f32 v209, v209, v63, v64
	v_max3_f32 v208, v208, v209, v49
	v_max_f32_e32 v208, v208, v65
	v_mov_b32_e32 v209, v208
	s_nop 1
	v_permlane32_swap_b32_e32 v208, v209
	v_max_f32_e32 v208, v208, v209
	v_cmp_ge_f32_e32 vcc, 0x41000000, v208
	s_cmp_eq_u64 vcc, exec
	s_cbranch_scc0 .Lad64_resc
.Lad64_exp:
	v_exp_f32_e32 v34, v34
	v_exp_f32_e32 v35, v35
	v_exp_f32_e32 v36, v36
	v_exp_f32_e32 v37, v37
	v_exp_f32_e32 v38, v38
	v_exp_f32_e32 v39, v39
	v_exp_f32_e32 v40, v40
	v_exp_f32_e32 v41, v41
	v_cvt_pk_bf16_f32 v220, v34, v35
	v_cvt_pk_bf16_f32 v221, v36, v37
	v_cvt_pk_bf16_f32 v222, v38, v39
	v_cvt_pk_bf16_f32 v223, v40, v41
	v_add_f32_e32 v208, v34, v35
	v_add_f32_e32 v209, v36, v37
	v_add_f32_e32 v208, v208, v38
	v_add_f32_e32 v209, v209, v39
	v_add_f32_e32 v208, v208, v40
	v_add_f32_e32 v209, v209, v41
	v_add_f32_e32 v96, v96, v208
	v_add_f32_e32 v96, v96, v209
	s_waitcnt lgkmcnt(10)
	v_mfma_f32_32x32x16_bf16 v[18:33], v[180:183], v[220:223], v[18:33]
	s_waitcnt lgkmcnt(8)
	v_mfma_f32_32x32x16_bf16 v[2:17], v[184:187], v[220:223], v[2:17]
	ds_read_b64_tr_b16 v[204:205], v134 offset:14336
	ds_read_b64_tr_b16 v[206:207], v134 offset:15360
	ds_read_b64_tr_b16 v[216:217], v117 offset:14336
	ds_read_b64_tr_b16 v[218:219], v117 offset:15360
	v_exp_f32_e32 v42, v42
	v_exp_f32_e32 v43, v43
	v_exp_f32_e32 v44, v44
	v_exp_f32_e32 v45, v45
	v_exp_f32_e32 v46, v46
	v_exp_f32_e32 v47, v47
	v_exp_f32_e32 v48, v48
	v_exp_f32_e32 v49, v49
	v_cvt_pk_bf16_f32 v224, v42, v43
	v_cvt_pk_bf16_f32 v225, v44, v45
	v_cvt_pk_bf16_f32 v226, v46, v47
	v_cvt_pk_bf16_f32 v227, v48, v49
	v_add_f32_e32 v208, v42, v43
	v_add_f32_e32 v209, v44, v45
	v_add_f32_e32 v208, v208, v46
	v_add_f32_e32 v209, v209, v47
	v_add_f32_e32 v208, v208, v48
	v_add_f32_e32 v209, v209, v49
	v_add_f32_e32 v96, v96, v208
	v_add_f32_e32 v96, v96, v209
	s_waitcnt lgkmcnt(10)
	v_mfma_f32_32x32x16_bf16 v[18:33], v[188:191], v[224:227], v[18:33]
	s_waitcnt lgkmcnt(8)
	v_mfma_f32_32x32x16_bf16 v[2:17], v[192:195], v[224:227], v[2:17]
	v_exp_f32_e32 v50, v50
	v_exp_f32_e32 v51, v51
	v_exp_f32_e32 v52, v52
	v_exp_f32_e32 v53, v53
	v_exp_f32_e32 v54, v54
	v_exp_f32_e32 v55, v55
	v_exp_f32_e32 v56, v56
	v_exp_f32_e32 v57, v57
	v_cvt_pk_bf16_f32 v228, v50, v51
	v_cvt_pk_bf16_f32 v229, v52, v53
	v_cvt_pk_bf16_f32 v230, v54, v55
	v_cvt_pk_bf16_f32 v231, v56, v57
	v_add_f32_e32 v208, v50, v51
	v_add_f32_e32 v209, v52, v53
	v_add_f32_e32 v208, v208, v54
	v_add_f32_e32 v209, v209, v55
	v_add_f32_e32 v208, v208, v56
	v_add_f32_e32 v209, v209, v57
	v_add_f32_e32 v96, v96, v208
	v_add_f32_e32 v96, v96, v209
	s_waitcnt lgkmcnt(6)
	v_mfma_f32_32x32x16_bf16 v[18:33], v[196:199], v[228:231], v[18:33]
	s_waitcnt lgkmcnt(4)
	v_mfma_f32_32x32x16_bf16 v[2:17], v[200:203], v[228:231], v[2:17]
	v_exp_f32_e32 v58, v58
	v_exp_f32_e32 v59, v59
	v_exp_f32_e32 v60, v60
	v_exp_f32_e32 v61, v61
	v_exp_f32_e32 v62, v62
	v_exp_f32_e32 v63, v63
	v_exp_f32_e32 v64, v64
	v_exp_f32_e32 v65, v65
	v_cvt_pk_bf16_f32 v232, v58, v59
	v_cvt_pk_bf16_f32 v233, v60, v61
	v_cvt_pk_bf16_f32 v234, v62, v63
	v_cvt_pk_bf16_f32 v235, v64, v65
	v_add_f32_e32 v208, v58, v59
	v_add_f32_e32 v209, v60, v61
	v_add_f32_e32 v208, v208, v62
	v_add_f32_e32 v209, v209, v63
	v_add_f32_e32 v208, v208, v64
	v_add_f32_e32 v209, v209, v65
	v_add_f32_e32 v96, v96, v208
	v_add_f32_e32 v96, v96, v209
	s_waitcnt lgkmcnt(2)
	v_mfma_f32_32x32x16_bf16 v[18:33], v[204:207], v[232:235], v[18:33]
	s_waitcnt lgkmcnt(0)
	v_mfma_f32_32x32x16_bf16 v[2:17], v[216:219], v[232:235], v[2:17]
	s_and_b32 s26, s24, 0x4000
	v_add3_u32 v134, s26, v106, v101
	v_add3_u32 v117, s26, v97, v99
	s_waitcnt vmcnt(1)
	ds_write_b128 v134, v[82:85]
	s_waitcnt vmcnt(0)
	ds_write_b128 v117, v[86:89] offset:8192
	s_add_i32 s10, s10, 1
	s_addk_i32 s24, 0x4000
	s_mov_b32 s25, s26
	s_cmp_eq_u32 s10, 39
	s_cbranch_scc1 .Lad64_nofetch
	s_cmp_lg_u32 s10, 7
	s_cbranch_scc1 .Lad64_ptr_ok
	v_add_u32_e32 v134, s11, v239
	v_add_u32_e32 v134, 0x180, v134
	v_mad_i64_i32 v[246:247], s[26:27], v134, s84, 0
	v_mov_b32_e32 v208, s70
	v_mov_b32_e32 v209, s71
	v_lshl_add_u64 v[208:209], v[246:247], 1, v[208:209]
	v_lshl_add_u64 v[208:209], v[208:209], 0, s[0:1]
	v_lshl_add_u64 v[240:241], v[92:93], 1, v[208:209]
	v_mov_b32_e32 v208, s6
	v_mov_b32_e32 v209, s7
	v_lshl_add_u64 v[208:209], v[246:247], 1, v[208:209]
	v_lshl_add_u64 v[208:209], v[208:209], 0, s[0:1]
	v_lshl_add_u64 v[242:243], v[208:209], 0, v[0:1]
	s_lshl_b32 s26, s84, 7
	v_mov_b32_e32 v244, s26
.Lad64_ptr_ok:
	global_load_dwordx4 v[82:85], v[240:241], off
	global_load_dwordx4 v[86:89], v[242:243], off
	v_lshl_add_u64 v[240:241], v[240:241], 0, v[244:245]
	v_lshl_add_u64 v[242:243], v[242:243], 0, v[244:245]
.Lad64_nofetch:
	v_add_u32_e32 v134, s25, v98
	v_add_u32_e32 v117, s25, v109
	v_add_u32_e32 v208, s25, v111
	v_add_u32_e32 v209, s25, v114
	s_cmp_lg_u32 s10, 39
	s_waitcnt lgkmcnt(0)
	s_barrier
	s_cbranch_scc1 .Lad64_top
	s_setprio 0
	s_branch .LBB0_345
